# stack + attention main-loop row-max chain trim (canonicalising v_max pairs and a zero add removed)
# baseline (speedup 1.0000x reference)
.LBB0_773:
	v_add_u32_e32 v1, s6, v238
	ds_read_b128 v[242:245], v209
	ds_read_b128 v[246:249], v209 offset:512
	ds_read_b64_tr_b16 v[196:197], v1 offset:24576
	ds_read_b64_tr_b16 v[198:199], v1 offset:25088
	s_waitcnt lgkmcnt(11)
	v_mfma_f32_32x32x16_bf16 v[112:127], v[192:195], v[140:143], v[48:63]
	v_add_f32_e32 v2, v80, v81
	v_add_f32_e32 v2, v82, v2
	v_add_f32_e32 v2, v83, v2
	v_add_f32_e32 v2, v84, v2
	v_add_f32_e32 v2, v85, v2
	v_cvt_pk_bf16_f32 v160, v80, v81
	v_cvt_pk_bf16_f32 v161, v82, v83
	ds_read_b64_tr_b16 v[192:193], v1 offset:28672
	ds_read_b64_tr_b16 v[194:195], v1 offset:29184
	s_waitcnt lgkmcnt(12)
	v_mfma_f32_32x32x16_bf16 v[96:111], v[188:191], v[140:143], v[48:63]
	v_add_f32_e32 v2, v86, v2
	v_add_f32_e32 v2, v87, v2
	v_add_f32_e32 v2, v88, v2
	v_add_f32_e32 v2, v89, v2
	v_cvt_pk_bf16_f32 v162, v84, v85
	v_cvt_pk_bf16_f32 v163, v86, v87
	ds_read_b64_tr_b16 v[188:189], v1 offset:25600
	ds_read_b64_tr_b16 v[190:191], v1 offset:26112
	s_waitcnt lgkmcnt(13)
	v_mfma_f32_32x32x16_bf16 v[112:127], v[184:187], v[136:139], v[112:127]
	v_add_f32_e32 v2, v90, v2
	v_add_f32_e32 v2, v91, v2
	v_add_f32_e32 v2, v92, v2
	v_add_f32_e32 v2, v93, v2
	v_cvt_pk_bf16_f32 v156, v88, v89
	v_cvt_pk_bf16_f32 v157, v90, v91
	ds_read_b64_tr_b16 v[84:85], v1 offset:29696
	ds_read_b64_tr_b16 v[86:87], v1 offset:30208
	s_waitcnt lgkmcnt(14)
	v_mfma_f32_32x32x16_bf16 v[96:111], v[180:183], v[136:139], v[96:111]
	v_add_f32_e32 v2, v94, v2
	v_add_f32_e32 v2, v95, v2
	v_add_f32_e32 v2, v64, v2
	v_add_f32_e32 v2, v65, v2
	v_cvt_pk_bf16_f32 v158, v92, v93
	v_cvt_pk_bf16_f32 v159, v94, v95
	ds_read_b64_tr_b16 v[80:81], v1 offset:26624
	ds_read_b64_tr_b16 v[82:83], v1 offset:27136
	s_waitcnt lgkmcnt(14)
	v_mfma_f32_32x32x16_bf16 v[112:127], v[176:179], v[132:135], v[112:127]
	v_add_f32_e32 v2, v66, v2
	v_add_f32_e32 v2, v67, v2
	v_add_f32_e32 v2, v68, v2
	v_add_f32_e32 v2, v69, v2
	v_cvt_pk_bf16_f32 v152, v64, v65
	v_cvt_pk_bf16_f32 v153, v66, v67
	ds_read_b64_tr_b16 v[10:11], v1 offset:30720
	ds_read_b64_tr_b16 v[12:13], v1 offset:31232
	v_mfma_f32_32x32x16_bf16 v[96:111], v[172:175], v[132:135], v[96:111]
	v_add_f32_e32 v2, v70, v2
	v_add_f32_e32 v2, v71, v2
	v_add_f32_e32 v2, v72, v2
	v_add_f32_e32 v2, v73, v2
	v_cvt_pk_bf16_f32 v154, v68, v69
	v_cvt_pk_bf16_f32 v155, v70, v71
	ds_read_b64_tr_b16 v[6:7], v1 offset:27648
	ds_read_b64_tr_b16 v[8:9], v1 offset:28160
	s_waitcnt lgkmcnt(14)
	v_mfma_f32_32x32x16_bf16 v[112:127], v[168:171], v[128:131], v[112:127]
	v_add_f32_e32 v2, v74, v2
	v_add_f32_e32 v2, v75, v2
	v_add_f32_e32 v2, v76, v2
	v_add_f32_e32 v14, v77, v2
	v_cvt_pk_bf16_f32 v148, v72, v73
	v_cvt_pk_bf16_f32 v149, v74, v75
	ds_read_b64_tr_b16 v[2:3], v1 offset:31744
	ds_read_b64_tr_b16 v[4:5], v1 offset:32256
	v_mfma_f32_32x32x16_bf16 v[96:111], v[164:167], v[128:131], v[96:111]
	v_add_f32_e32 v1, v78, v14
	v_add_f32_e32 v1, v79, v1
	v_cvt_pk_bf16_f32 v150, v76, v77
	v_cvt_pk_bf16_f32 v151, v78, v79
	v_mfma_f32_32x32x16_bf16 v[112:127], v[242:245], v[144:147], v[112:127]
	v_mfma_f32_32x32x16_bf16 v[96:111], v[246:249], v[144:147], v[96:111]
	v_lshl_add_u64 v[14:15], v[206:207], 0, s[80:81]
	s_add_i32 s6, s13, s20
	s_mov_b32 s7, m0
	s_mov_b32 m0, s6
	s_nop 0
	global_load_lds_dwordx4 v[14:15], off
	s_mov_b32 m0, s7
	v_lshl_add_u64 v[14:15], v[204:205], 0, s[80:81]
	s_add_i32 s6, s11, s21
	s_mov_b32 s7, m0
	s_mov_b32 m0, s6
	s_nop 0
	global_load_lds_dwordx4 v[14:15], off
	s_mov_b32 m0, s7
	s_nop 6
	v_max_f32_e32 v14, v112, v113
	v_max3_f32 v15, v114, v115, v97
	v_max3_f32 v14, v14, v96, v98
	v_max3_f32 v14, v14, v99, v116
	v_max3_f32 v15, v15, v118, v119
	v_max3_f32 v14, v14, v117, v100
	v_max3_f32 v15, v15, v102, v103
	v_max3_f32 v14, v14, v101, v120
	v_max3_f32 v15, v15, v122, v123
	v_max3_f32 v14, v14, v121, v104
	v_max3_f32 v15, v15, v106, v107
	v_max3_f32 v14, v14, v105, v124
	v_max3_f32 v15, v15, v126, v127
	v_max3_f32 v64, v14, v125, v108
	v_max3_f32 v15, v15, v110, v111
	v_add_f32_e32 v14, v240, v1
	v_max3_f32 v1, v64, v109, v15
	v_mov_b32_e32 v15, v1
	s_nop 1
	v_permlane32_swap_b32_e32 v1, v15
	v_max_f32_e32 v1, v1, v15
	v_cmp_lt_f32_e32 vcc, s88, v1
	s_cmp_lg_u64 vcc, 0
	s_cselect_b64 s[6:7], -1, 0
	s_cbranch_vccnz .LBB0_781

.LBB0_776:
	s_add_i32 s6, s11, 0x2000
	s_cmpk_lg_i32 s11, 0x4000
	s_cselect_b32 s23, s6, 0
	v_add_u32_e32 v4, s13, v238
	ds_read_b128 v[240:243], v209 offset:1024
	ds_read_b128 v[244:247], v209 offset:1536
	ds_read_b64_tr_b16 v[172:173], v4 offset:24576
	ds_read_b64_tr_b16 v[174:175], v4 offset:25088
	s_waitcnt lgkmcnt(11)
	v_mfma_f32_32x32x16_bf16 v[80:95], v[64:67], v[140:143], v[48:63]
	v_add_f32_e32 v2, v112, v113
	v_add_f32_e32 v2, v114, v2
	v_add_f32_e32 v2, v115, v2
	v_add_f32_e32 v2, v116, v2
	v_add_f32_e32 v2, v117, v2
	v_cvt_pk_bf16_f32 v160, v112, v113
	v_cvt_pk_bf16_f32 v161, v114, v115
	ds_read_b64_tr_b16 v[168:169], v4 offset:28672
	ds_read_b64_tr_b16 v[170:171], v4 offset:29184
	s_waitcnt lgkmcnt(12)
	v_mfma_f32_32x32x16_bf16 v[64:79], v[164:167], v[140:143], v[48:63]
	v_add_f32_e32 v2, v118, v2
	v_add_f32_e32 v2, v119, v2
	v_add_f32_e32 v2, v120, v2
	v_add_f32_e32 v2, v121, v2
	v_cvt_pk_bf16_f32 v162, v116, v117
	v_cvt_pk_bf16_f32 v163, v118, v119
	ds_read_b64_tr_b16 v[164:165], v4 offset:25600
	ds_read_b64_tr_b16 v[166:167], v4 offset:26112
	s_waitcnt lgkmcnt(13)
	v_mfma_f32_32x32x16_bf16 v[80:95], v[196:199], v[136:139], v[80:95]
	v_add_f32_e32 v2, v122, v2
	v_add_f32_e32 v2, v123, v2
	v_add_f32_e32 v2, v124, v2
	v_add_f32_e32 v2, v125, v2
	v_cvt_pk_bf16_f32 v156, v120, v121
	v_cvt_pk_bf16_f32 v157, v122, v123
	ds_read_b64_tr_b16 v[116:117], v4 offset:29696
	ds_read_b64_tr_b16 v[118:119], v4 offset:30208
	s_waitcnt lgkmcnt(14)
	v_mfma_f32_32x32x16_bf16 v[64:79], v[188:191], v[136:139], v[64:79]
	v_add_f32_e32 v2, v126, v2
	v_add_f32_e32 v2, v127, v2
	v_add_f32_e32 v2, v96, v2
	v_add_f32_e32 v2, v97, v2
	v_cvt_pk_bf16_f32 v158, v124, v125
	v_cvt_pk_bf16_f32 v159, v126, v127
	ds_read_b64_tr_b16 v[112:113], v4 offset:26624
	ds_read_b64_tr_b16 v[114:115], v4 offset:27136
	s_waitcnt lgkmcnt(14)
	v_mfma_f32_32x32x16_bf16 v[80:95], v[192:195], v[132:135], v[80:95]
	v_add_f32_e32 v2, v98, v2
	v_add_f32_e32 v2, v99, v2
	v_add_f32_e32 v2, v100, v2
	v_add_f32_e32 v2, v101, v2
	v_cvt_pk_bf16_f32 v152, v96, v97
	v_cvt_pk_bf16_f32 v153, v98, v99
	ds_read_b64_tr_b16 v[10:11], v4 offset:30720
	ds_read_b64_tr_b16 v[12:13], v4 offset:31232
	v_mfma_f32_32x32x16_bf16 v[64:79], v[180:183], v[132:135], v[64:79]
	v_add_f32_e32 v2, v102, v2
	v_add_f32_e32 v2, v103, v2
	v_add_f32_e32 v2, v104, v2
	v_add_f32_e32 v2, v105, v2
	v_cvt_pk_bf16_f32 v154, v100, v101
	v_cvt_pk_bf16_f32 v155, v102, v103
	ds_read_b64_tr_b16 v[6:7], v4 offset:27648
	ds_read_b64_tr_b16 v[8:9], v4 offset:28160
	s_waitcnt lgkmcnt(14)
	v_mfma_f32_32x32x16_bf16 v[80:95], v[184:187], v[128:131], v[80:95]
	v_add_f32_e32 v2, v106, v2
	v_add_f32_e32 v2, v107, v2
	v_add_f32_e32 v2, v108, v2
	v_add_f32_e32 v15, v109, v2
	v_cvt_pk_bf16_f32 v148, v104, v105
	v_cvt_pk_bf16_f32 v149, v106, v107
	ds_read_b64_tr_b16 v[2:3], v4 offset:31744
	ds_read_b64_tr_b16 v[4:5], v4 offset:32256
	v_mfma_f32_32x32x16_bf16 v[64:79], v[176:179], v[128:131], v[64:79]
	v_add_f32_e32 v15, v110, v15
	v_add_f32_e32 v15, v111, v15
	v_add_f32_e32 v15, 0, v15
	v_cvt_pk_bf16_f32 v150, v108, v109
	v_cvt_pk_bf16_f32 v151, v110, v111
	v_mfma_f32_32x32x16_bf16 v[80:95], v[240:243], v[144:147], v[80:95]
	v_mfma_f32_32x32x16_bf16 v[64:79], v[244:247], v[144:147], v[64:79]
	s_nop 10
	v_max_f32_e32 v96, v80, v81
	v_max3_f32 v97, v82, v83, v65
	v_max3_f32 v96, v96, v64, v66
	v_max3_f32 v96, v96, v67, v84
	v_max3_f32 v97, v97, v86, v87
	v_max3_f32 v96, v96, v85, v68
	v_max3_f32 v97, v97, v70, v71
	v_max3_f32 v96, v96, v69, v88
	v_max3_f32 v97, v97, v90, v91
	v_max3_f32 v96, v96, v89, v72
	v_max3_f32 v97, v97, v74, v75
	v_max3_f32 v96, v96, v73, v92
	v_max3_f32 v97, v97, v94, v95
	v_max3_f32 v96, v96, v93, v76
	v_max3_f32 v97, v97, v78, v79
	v_add_f32_e32 v240, v14, v15
	v_max3_f32 v14, v96, v77, v97
	v_mov_b32_e32 v15, v14
	s_nop 1
	v_permlane32_swap_b32_e32 v14, v15
	v_max_f32_e32 v15, v15, v15
	v_max_f32_e32 v14, v14, v14
	s_add_i32 s6, s11, s20
	s_mov_b32 s7, m0
	s_mov_b32 m0, s6
	s_nop 0
	global_load_lds_dwordx4 v[206:207], off
	s_mov_b32 m0, s7
	v_max_f32_e32 v14, v14, v15
	s_add_i32 s6, s23, s21
	s_mov_b32 s7, m0
	s_mov_b32 m0, s6
	s_nop 0
	global_load_lds_dwordx4 v[204:205], off
	s_mov_b32 m0, s7
	v_cmp_lt_f32_e32 vcc, s88, v14
	s_cmp_lg_u64 vcc, 0
	s_cselect_b64 s[6:7], -1, 0
	s_cbranch_vccnz .LBB0_784
